# as v24 (barrier four MFMAs early, late priority raise) but all six staging loads of the 6-load super-phase stay in the load segment
# speedup vs baseline: 1.0032x; 1.0032x over previous
; #define PG8_STAGE(bufoff, gbase, voff) do { _Pragma("unroll") for (int _i = 0; _i < 2; ++_i) \
;         __builtin_amdgcn_global_load_lds((const unsigned*)((const char*)(gbase) + (voff)[_i]), (PG8_LAS unsigned*)(lds + (bufoff) + ldsw + _i * 8192), 16, 0, 0); } while (0)
; #define PG8_LDA(dst, b, h) do { _Pragma("unroll") for (int m = 0; m < 4; ++m) _Pragma("unroll") for (int k = 0; k < 2; ++k) dst[m][k] = *(const PG8_LAS bf16x8*)(lds + PG8_SA(b, h) + aoff + m * 2048 + k * 1024); } while (0)
; #define PG8_LDB(dst, b, h) do { _Pragma("unroll") for (int n = 0; n < 2; ++n) _Pragma("unroll") for (int k = 0; k < 2; ++k) dst[n][k] = *(const PG8_LAS bf16x8*)(lds + PG8_SB(b, h) + boff + n * 2048 + k * 1024); } while (0)
; #define PG8_MMA(ai, bj, At, Bt) do { __builtin_amdgcn_s_setprio(1); _Pragma("unroll") for (int m = 0; m < 4; ++m) _Pragma("unroll") for (int n = 0; n < 2; ++n) _Pragma("unroll") for (int k = 0; k < 2; ++k) \
;         acc[ai][bj][m][n] = __builtin_amdgcn_mfma_f32_16x16x32_bf16(Bt[n][k], At[m][k], acc[ai][bj][m][n], 0, 0, 0); __builtin_amdgcn_s_setprio(0); } while (0)
; #define PG8_WAIT_V(n) asm volatile("s_waitcnt vmcnt(" #n ")" ::: "memory")
; #define PG8_BAR __builtin_amdgcn_s_barrier()
; template <class Epi, class Sched, bool ALIGN_EPI = false, bool SP2 = false>
; __device__ __forceinline__ void gemm_phase(PG8_LAS unsigned char* lds, const Gemm g, const Sched& S, const Epi& E) {
;     ...
;         for (int t = 0; t < nt; t += 2) {
;             const bool last = (t == nt - 2);
;             const char* a1 = cA + (size_t)(t + 1) * kstep;
;             const char* a2 = last ? nA : cA + (size_t)(t + 2) * kstep; const char* b2 = last ? nB : cB + (size_t)(t + 2) * kstep;
;             const char* a3 = a2 + kstep; const char* b3 = b2 + kstep;
;             if (last && has_next) S.a_ready(nxt);
;             if constexpr (SP2) {
;             PG8_LDB(B0, 0, 0); PG8_LDB(B1, 0, 1); PG8_SCHED; PG8_LDA(At, 0, 0); PG8_STAGE(PG8_SA(1, 1), a1 + hstep, voffA);
;             PG8_WAIT_V(8); PG8_WAIT_L(0); PG8_BAR; PG8_MMA(0, 0, At, B0); PG8_MMA(0, 1, At, B1); PG8_BAR; PG8_SCHED;
;             PG8_LDA(At, 0, 1); PG8_STAGE(PG8_SB(0, 0), b2, voffB); PG8_STAGE(PG8_SB(0, 1), b2 + hstep, voffB); PG8_STAGE(PG8_SA(0, 0), a2, voffA);
;             PG8_WAIT_V(8); PG8_WAIT_L(0); PG8_BAR; PG8_MMA(1, 0, At, B0); PG8_MMA(1, 1, At, B1); PG8_BAR; PG8_SCHED;
.LBB0_165:
	s_add_u32 s16, s8, 0xfffc0080
	s_addc_u32 s17, s9, -1
	s_add_i32 s18, 0, 0x10000
	s_cmp_eq_u32 s55, 12
	s_cselect_b32 s43, s14, s17
	s_cselect_b32 s42, s15, s16
	v_add_u32_e32 v0, s18, v194
	s_cselect_b32 s41, s13, s54
	s_cselect_b32 s40, s25, s53
	s_add_i32 s19, 0, 0x14000
	ds_read_b128 v[136:139], v0
	ds_read_b128 v[140:143], v0 offset:1024
	ds_read_b128 v[144:147], v0 offset:2048
	ds_read_b128 v[148:151], v0 offset:3072
	v_add_u32_e32 v0, s19, v194
	ds_read_b128 v[152:155], v0
	ds_read_b128 v[186:189], v0 offset:1024
	ds_read_b128 v[190:193], v0 offset:2048
	ds_read_b128 v[198:201], v0 offset:3072
	v_lshl_add_u64 v[2:3], s[8:9], 0, v[182:183]
	s_add_i32 m0, s45, 0xc000
	ds_read_b128 v[210:213], v196
	ds_read_b128 v[214:217], v196 offset:1024
	ds_read_b128 v[218:221], v196 offset:2048
	ds_read_b128 v[222:225], v196 offset:3072
	ds_read_b128 v[226:229], v196 offset:4096
	ds_read_b128 v[230:233], v196 offset:5120
	ds_read_b128 v[234:237], v196 offset:6144
	ds_read_b128 v[238:241], v196 offset:7168
	global_load_lds_dwordx4 v[2:3], off
	v_lshl_add_u64 v[2:3], s[8:9], 0, v[184:185]
	s_add_i32 m0, s45, 0xe000
	s_nop 0
	global_load_lds_dwordx4 v[2:3], off
	s_waitcnt vmcnt(8)
	s_waitcnt lgkmcnt(0)
	s_barrier
	s_waitcnt lgkmcnt(0)
	v_mfma_f32_16x16x32_bf16 v[132:135], v[136:139], v[210:213], v[132:135]
	v_mfma_f32_16x16x32_bf16 v[128:131], v[144:147], v[210:213], v[128:131]
	v_mfma_f32_16x16x32_bf16 v[124:127], v[136:139], v[218:221], v[124:127]
	v_mfma_f32_16x16x32_bf16 v[120:123], v[144:147], v[218:221], v[120:123]
	s_setprio 1
	v_mfma_f32_16x16x32_bf16 v[116:119], v[136:139], v[226:229], v[116:119]
	v_mfma_f32_16x16x32_bf16 v[112:115], v[144:147], v[226:229], v[112:115]
	v_mfma_f32_16x16x32_bf16 v[108:111], v[136:139], v[234:237], v[108:111]
	v_mfma_f32_16x16x32_bf16 v[104:107], v[144:147], v[234:237], v[104:107]
	v_mfma_f32_16x16x32_bf16 v[132:135], v[140:143], v[214:217], v[132:135]
	v_mfma_f32_16x16x32_bf16 v[128:131], v[148:151], v[214:217], v[128:131]
	v_mfma_f32_16x16x32_bf16 v[124:127], v[140:143], v[222:225], v[124:127]
	v_mfma_f32_16x16x32_bf16 v[120:123], v[148:151], v[222:225], v[120:123]
	v_mfma_f32_16x16x32_bf16 v[116:119], v[140:143], v[230:233], v[116:119]
	v_mfma_f32_16x16x32_bf16 v[112:115], v[148:151], v[230:233], v[112:115]
	v_mfma_f32_16x16x32_bf16 v[108:111], v[140:143], v[238:241], v[108:111]
	v_mfma_f32_16x16x32_bf16 v[104:107], v[148:151], v[238:241], v[104:107]
	s_setprio 0
	s_setprio 1
	v_mfma_f32_16x16x32_bf16 v[84:87], v[152:155], v[210:213], v[84:87]
	v_mfma_f32_16x16x32_bf16 v[76:79], v[190:193], v[210:213], v[76:79]
	v_mfma_f32_16x16x32_bf16 v[68:71], v[152:155], v[218:221], v[68:71]
	v_mfma_f32_16x16x32_bf16 v[64:67], v[190:193], v[218:221], v[64:67]
	v_mfma_f32_16x16x32_bf16 v[52:55], v[152:155], v[226:229], v[52:55]
	v_mfma_f32_16x16x32_bf16 v[48:51], v[190:193], v[226:229], v[48:51]
	v_mfma_f32_16x16x32_bf16 v[44:47], v[152:155], v[234:237], v[44:47]
	v_mfma_f32_16x16x32_bf16 v[40:43], v[190:193], v[234:237], v[40:43]
	v_mfma_f32_16x16x32_bf16 v[84:87], v[186:189], v[214:217], v[84:87]
	v_mfma_f32_16x16x32_bf16 v[76:79], v[198:201], v[214:217], v[76:79]
	v_mfma_f32_16x16x32_bf16 v[68:71], v[186:189], v[222:225], v[68:71]
	v_mfma_f32_16x16x32_bf16 v[64:67], v[198:201], v[222:225], v[64:67]
	s_barrier
	v_mfma_f32_16x16x32_bf16 v[52:55], v[186:189], v[230:233], v[52:55]
	v_mfma_f32_16x16x32_bf16 v[48:51], v[198:201], v[230:233], v[48:51]
	v_mfma_f32_16x16x32_bf16 v[44:47], v[186:189], v[238:241], v[44:47]
	v_mfma_f32_16x16x32_bf16 v[40:43], v[198:201], v[238:241], v[40:43]
	s_setprio 0
	s_add_i32 s16, s18, s44
	v_lshl_add_u64 v[2:3], s[40:41], 0, v[162:163]
	s_mov_b32 m0, s16
	ds_read_b128 v[210:213], v196 offset:16384
	ds_read_b128 v[214:217], v196 offset:17408
	ds_read_b128 v[218:221], v196 offset:18432
	ds_read_b128 v[222:225], v196 offset:19456
	ds_read_b128 v[226:229], v196 offset:20480
	ds_read_b128 v[230:233], v196 offset:21504
	ds_read_b128 v[234:237], v196 offset:22528
	ds_read_b128 v[238:241], v196 offset:23552
	global_load_lds_dwordx4 v[2:3], off
	s_add_i32 m0, s16, 0x2000
	s_add_u32 s16, s40, 0x40000
	v_lshl_add_u64 v[156:157], s[40:41], 0, v[158:159]
	s_addc_u32 s17, s41, 0
	s_add_i32 s18, s19, s44
	global_load_lds_dwordx4 v[156:157], off
	v_lshl_add_u64 v[242:243], s[16:17], 0, v[162:163]
	s_mov_b32 m0, s18
	v_lshl_add_u64 v[244:245], s[42:43], 0, v[160:161]
	global_load_lds_dwordx4 v[242:243], off
	v_lshl_add_u64 v[242:243], s[16:17], 0, v[158:159]
	s_add_i32 m0, s18, 0x2000
	s_nop 0
	global_load_lds_dwordx4 v[242:243], off
	v_lshl_add_u64 v[242:243], s[42:43], 0, v[178:179]
	s_mov_b32 m0, s45
	s_nop 0
	global_load_lds_dwordx4 v[242:243], off
	s_mov_b32 m0, s46
	s_nop 0
	global_load_lds_dwordx4 v[244:245], off
	s_waitcnt vmcnt(8)
	s_waitcnt lgkmcnt(0)
	s_barrier
; #define PG8_STAGE(bufoff, gbase, voff) do { _Pragma("unroll") for (int _i = 0; _i < 2; ++_i) \
;         __builtin_amdgcn_global_load_lds((const unsigned*)((const char*)(gbase) + (voff)[_i]), (PG8_LAS unsigned*)(lds + (bufoff) + ldsw + _i * 8192), 16, 0, 0); } while (0)
; #define PG8_LDA(dst, b, h) do { _Pragma("unroll") for (int m = 0; m < 4; ++m) _Pragma("unroll") for (int k = 0; k < 2; ++k) dst[m][k] = *(const PG8_LAS bf16x8*)(lds + PG8_SA(b, h) + aoff + m * 2048 + k * 1024); } while (0)
; #define PG8_LDB(dst, b, h) do { _Pragma("unroll") for (int n = 0; n < 2; ++n) _Pragma("unroll") for (int k = 0; k < 2; ++k) dst[n][k] = *(const PG8_LAS bf16x8*)(lds + PG8_SB(b, h) + boff + n * 2048 + k * 1024); } while (0)
; #define PG8_MMA(ai, bj, At, Bt) do { __builtin_amdgcn_s_setprio(1); _Pragma("unroll") for (int m = 0; m < 4; ++m) _Pragma("unroll") for (int n = 0; n < 2; ++n) _Pragma("unroll") for (int k = 0; k < 2; ++k) \
;         acc[ai][bj][m][n] = __builtin_amdgcn_mfma_f32_16x16x32_bf16(Bt[n][k], At[m][k], acc[ai][bj][m][n], 0, 0, 0); __builtin_amdgcn_s_setprio(0); } while (0)
; #define PG8_WAIT_V(n) asm volatile("s_waitcnt vmcnt(" #n ")" ::: "memory")
; #define PG8_WAIT_L(n) asm volatile("s_waitcnt lgkmcnt(" #n ")" ::: "memory")
; #define PG8_BAR __builtin_amdgcn_s_barrier()
; #define PG8_SCHED __builtin_amdgcn_sched_barrier(0)
; template <class Epi, class Sched, bool ALIGN_EPI = false, bool SP2 = false>
; __device__ __forceinline__ void gemm_phase(PG8_LAS unsigned char* lds, const Gemm g, const Sched& S, const Epi& E) {
;     ...
;             PG8_WAIT_V(8); PG8_WAIT_L(0); PG8_BAR; PG8_MMA(1, 0, At, B0); PG8_MMA(1, 1, At, B1); PG8_BAR; PG8_SCHED;
;             PG8_LDB(B0, 1, 0); PG8_LDB(B1, 1, 1); PG8_SCHED; PG8_LDA(At, 1, 0); PG8_STAGE(PG8_SA(0, 1), a2 + hstep, voffA);
;             PG8_WAIT_V(8); PG8_WAIT_L(0); PG8_BAR; PG8_MMA(0, 0, At, B0); PG8_MMA(0, 1, At, B1); PG8_BAR; PG8_SCHED;
	s_waitcnt lgkmcnt(0)
	v_mfma_f32_16x16x32_bf16 v[100:103], v[136:139], v[210:213], v[100:103]
	v_mfma_f32_16x16x32_bf16 v[96:99], v[144:147], v[210:213], v[96:99]
	v_mfma_f32_16x16x32_bf16 v[92:95], v[136:139], v[218:221], v[92:95]
	v_mfma_f32_16x16x32_bf16 v[88:91], v[144:147], v[218:221], v[88:91]
	s_setprio 1
	v_mfma_f32_16x16x32_bf16 v[80:83], v[136:139], v[226:229], v[80:83]
	v_mfma_f32_16x16x32_bf16 v[72:75], v[144:147], v[226:229], v[72:75]
	v_mfma_f32_16x16x32_bf16 v[60:63], v[136:139], v[234:237], v[60:63]
	v_mfma_f32_16x16x32_bf16 v[56:59], v[144:147], v[234:237], v[56:59]
	v_mfma_f32_16x16x32_bf16 v[100:103], v[140:143], v[214:217], v[100:103]
	v_mfma_f32_16x16x32_bf16 v[96:99], v[148:151], v[214:217], v[96:99]
	v_mfma_f32_16x16x32_bf16 v[92:95], v[140:143], v[222:225], v[92:95]
	v_mfma_f32_16x16x32_bf16 v[88:91], v[148:151], v[222:225], v[88:91]
	v_mfma_f32_16x16x32_bf16 v[80:83], v[140:143], v[230:233], v[80:83]
	v_mfma_f32_16x16x32_bf16 v[72:75], v[148:151], v[230:233], v[72:75]
	v_mfma_f32_16x16x32_bf16 v[60:63], v[140:143], v[238:241], v[60:63]
	v_mfma_f32_16x16x32_bf16 v[56:59], v[148:151], v[238:241], v[56:59]
	s_setprio 0
	s_setprio 1
	v_mfma_f32_16x16x32_bf16 v[36:39], v[152:155], v[210:213], v[36:39]
	v_mfma_f32_16x16x32_bf16 v[32:35], v[190:193], v[210:213], v[32:35]
	v_mfma_f32_16x16x32_bf16 v[28:31], v[152:155], v[218:221], v[28:31]
	v_mfma_f32_16x16x32_bf16 v[24:27], v[190:193], v[218:221], v[24:27]
	v_mfma_f32_16x16x32_bf16 v[20:23], v[152:155], v[226:229], v[20:23]
	v_mfma_f32_16x16x32_bf16 v[16:19], v[190:193], v[226:229], v[16:19]
	v_mfma_f32_16x16x32_bf16 v[12:15], v[152:155], v[234:237], v[12:15]
	v_mfma_f32_16x16x32_bf16 v[8:11], v[190:193], v[234:237], v[8:11]
	v_mfma_f32_16x16x32_bf16 v[36:39], v[186:189], v[214:217], v[36:39]
	v_mfma_f32_16x16x32_bf16 v[32:35], v[198:201], v[214:217], v[32:35]
	v_mfma_f32_16x16x32_bf16 v[28:31], v[186:189], v[222:225], v[28:31]
	v_mfma_f32_16x16x32_bf16 v[24:27], v[198:201], v[222:225], v[24:27]
	s_barrier
	v_mfma_f32_16x16x32_bf16 v[20:23], v[186:189], v[230:233], v[20:23]
	v_mfma_f32_16x16x32_bf16 v[16:19], v[198:201], v[230:233], v[16:19]
	v_mfma_f32_16x16x32_bf16 v[12:15], v[186:189], v[238:241], v[12:15]
	v_mfma_f32_16x16x32_bf16 v[8:11], v[198:201], v[238:241], v[8:11]
	s_setprio 0
	s_add_i32 s18, 0, 0x18000
	v_add_u32_e32 v0, s18, v194
	ds_read_b128 v[136:139], v0
	ds_read_b128 v[140:143], v0 offset:1024
	ds_read_b128 v[144:147], v0 offset:2048
	ds_read_b128 v[148:151], v0 offset:3072
	v_add_u32_e32 v0, s33, v194
	ds_read_b128 v[152:155], v0
	ds_read_b128 v[186:189], v0 offset:1024
	ds_read_b128 v[190:193], v0 offset:2048
	ds_read_b128 v[198:201], v0 offset:3072
	s_add_u32 s16, s42, 0x40000
	s_addc_u32 s17, s43, 0
	s_mov_b32 m0, s47
	v_lshl_add_u64 v[246:247], s[16:17], 0, v[178:179]
	ds_read_b128 v[210:213], v196 offset:32768
	ds_read_b128 v[214:217], v196 offset:33792
	ds_read_b128 v[218:221], v196 offset:34816
	ds_read_b128 v[222:225], v196 offset:35840
	ds_read_b128 v[226:229], v196 offset:36864
	ds_read_b128 v[230:233], v196 offset:37888
	ds_read_b128 v[234:237], v196 offset:38912
	ds_read_b128 v[238:241], v196 offset:39936
	global_load_lds_dwordx4 v[246:247], off
	v_lshl_add_u64 v[246:247], s[16:17], 0, v[160:161]
	s_mov_b32 m0, s48
	s_nop 0
	global_load_lds_dwordx4 v[246:247], off
	s_waitcnt vmcnt(8)
	s_waitcnt lgkmcnt(0)
	s_barrier
	s_waitcnt lgkmcnt(0)
	v_mfma_f32_16x16x32_bf16 v[132:135], v[136:139], v[210:213], v[132:135]
	v_mfma_f32_16x16x32_bf16 v[128:131], v[144:147], v[210:213], v[128:131]
	v_mfma_f32_16x16x32_bf16 v[124:127], v[136:139], v[218:221], v[124:127]
	v_mfma_f32_16x16x32_bf16 v[120:123], v[144:147], v[218:221], v[120:123]
	s_setprio 1
	v_mfma_f32_16x16x32_bf16 v[116:119], v[136:139], v[226:229], v[116:119]
	v_mfma_f32_16x16x32_bf16 v[112:115], v[144:147], v[226:229], v[112:115]
	v_mfma_f32_16x16x32_bf16 v[108:111], v[136:139], v[234:237], v[108:111]
	v_mfma_f32_16x16x32_bf16 v[104:107], v[144:147], v[234:237], v[104:107]
	v_mfma_f32_16x16x32_bf16 v[132:135], v[140:143], v[214:217], v[132:135]
	v_mfma_f32_16x16x32_bf16 v[128:131], v[148:151], v[214:217], v[128:131]
	v_mfma_f32_16x16x32_bf16 v[124:127], v[140:143], v[222:225], v[124:127]
	v_mfma_f32_16x16x32_bf16 v[120:123], v[148:151], v[222:225], v[120:123]
	v_mfma_f32_16x16x32_bf16 v[116:119], v[140:143], v[230:233], v[116:119]
	v_mfma_f32_16x16x32_bf16 v[112:115], v[148:151], v[230:233], v[112:115]
	v_mfma_f32_16x16x32_bf16 v[108:111], v[140:143], v[238:241], v[108:111]
	v_mfma_f32_16x16x32_bf16 v[104:107], v[148:151], v[238:241], v[104:107]
	s_setprio 0
	s_setprio 1
	v_mfma_f32_16x16x32_bf16 v[84:87], v[152:155], v[210:213], v[84:87]
	v_mfma_f32_16x16x32_bf16 v[76:79], v[190:193], v[210:213], v[76:79]
	v_mfma_f32_16x16x32_bf16 v[68:71], v[152:155], v[218:221], v[68:71]
	v_mfma_f32_16x16x32_bf16 v[64:67], v[190:193], v[218:221], v[64:67]
	v_mfma_f32_16x16x32_bf16 v[52:55], v[152:155], v[226:229], v[52:55]
	v_mfma_f32_16x16x32_bf16 v[48:51], v[190:193], v[226:229], v[48:51]
	v_mfma_f32_16x16x32_bf16 v[44:47], v[152:155], v[234:237], v[44:47]
	v_mfma_f32_16x16x32_bf16 v[40:43], v[190:193], v[234:237], v[40:43]
	v_mfma_f32_16x16x32_bf16 v[84:87], v[186:189], v[214:217], v[84:87]
	v_mfma_f32_16x16x32_bf16 v[76:79], v[198:201], v[214:217], v[76:79]
	v_mfma_f32_16x16x32_bf16 v[68:71], v[186:189], v[222:225], v[68:71]
	v_mfma_f32_16x16x32_bf16 v[64:67], v[198:201], v[222:225], v[64:67]
	s_barrier
; #define PG8_STAGE(bufoff, gbase, voff) do { _Pragma("unroll") for (int _i = 0; _i < 2; ++_i) \
;         __builtin_amdgcn_global_load_lds((const unsigned*)((const char*)(gbase) + (voff)[_i]), (PG8_LAS unsigned*)(lds + (bufoff) + ldsw + _i * 8192), 16, 0, 0); } while (0)
; #define PG8_LDA(dst, b, h) do { _Pragma("unroll") for (int m = 0; m < 4; ++m) _Pragma("unroll") for (int k = 0; k < 2; ++k) dst[m][k] = *(const PG8_LAS bf16x8*)(lds + PG8_SA(b, h) + aoff + m * 2048 + k * 1024); } while (0)
; #define PG8_MMA(ai, bj, At, Bt) do { __builtin_amdgcn_s_setprio(1); _Pragma("unroll") for (int m = 0; m < 4; ++m) _Pragma("unroll") for (int n = 0; n < 2; ++n) _Pragma("unroll") for (int k = 0; k < 2; ++k) \
;         acc[ai][bj][m][n] = __builtin_amdgcn_mfma_f32_16x16x32_bf16(Bt[n][k], At[m][k], acc[ai][bj][m][n], 0, 0, 0); __builtin_amdgcn_s_setprio(0); } while (0)
; #define PG8_WAIT_V(n) asm volatile("s_waitcnt vmcnt(" #n ")" ::: "memory")
; #define PG8_WAIT_L(n) asm volatile("s_waitcnt lgkmcnt(" #n ")" ::: "memory")
; #define PG8_BAR __builtin_amdgcn_s_barrier()
; #define PG8_SCHED __builtin_amdgcn_sched_barrier(0)
; template <class Epi, class Sched, bool ALIGN_EPI = false, bool SP2 = false>
; __device__ __forceinline__ void gemm_phase(PG8_LAS unsigned char* lds, const Gemm g, const Sched& S, const Epi& E) {
;     ...
;             PG8_WAIT_V(8); PG8_WAIT_L(0); PG8_BAR; PG8_MMA(0, 0, At, B0); PG8_MMA(0, 1, At, B1); PG8_BAR; PG8_SCHED;
;             PG8_LDA(At, 1, 1); PG8_STAGE(PG8_SB(1, 0), b3, voffB); PG8_STAGE(PG8_SB(1, 1), b3 + hstep, voffB); PG8_STAGE(PG8_SA(1, 0), a3, voffA);
;             PG8_WAIT_V(8); PG8_WAIT_L(0); PG8_BAR; PG8_MMA(1, 0, At, B0); PG8_MMA(1, 1, At, B1); PG8_BAR; PG8_SCHED;
	v_mfma_f32_16x16x32_bf16 v[52:55], v[186:189], v[230:233], v[52:55]
	v_mfma_f32_16x16x32_bf16 v[48:51], v[198:201], v[230:233], v[48:51]
	v_mfma_f32_16x16x32_bf16 v[44:47], v[186:189], v[238:241], v[44:47]
	v_mfma_f32_16x16x32_bf16 v[40:43], v[198:201], v[238:241], v[40:43]
	s_setprio 0
	s_add_i32 s16, s18, s44
	v_lshl_add_u64 v[2:3], v[2:3], 0, s[20:21]
	s_mov_b32 m0, s16
	ds_read_b128 v[210:213], v196 offset:49152
	ds_read_b128 v[214:217], v196 offset:50176
	ds_read_b128 v[218:221], v196 offset:51200
	ds_read_b128 v[222:225], v196 offset:52224
	ds_read_b128 v[226:229], v196 offset:53248
	ds_read_b128 v[230:233], v196 offset:54272
	ds_read_b128 v[234:237], v196 offset:55296
	ds_read_b128 v[238:241], v196 offset:56320
	global_load_lds_dwordx4 v[2:3], off
	s_add_i32 m0, s16, 0x2000
	s_add_u32 s16, s40, 0x40080
	v_lshl_add_u64 v[2:3], v[156:157], 0, s[20:21]
	s_addc_u32 s17, s41, 0
	s_add_i32 s18, s33, s44
	global_load_lds_dwordx4 v[2:3], off
	v_lshl_add_u64 v[2:3], s[16:17], 0, v[162:163]
	s_mov_b32 m0, s18
	s_nop 0
	global_load_lds_dwordx4 v[2:3], off
	v_lshl_add_u64 v[2:3], s[16:17], 0, v[158:159]
	s_add_i32 m0, s18, 0x2000
	s_nop 0
	global_load_lds_dwordx4 v[2:3], off
	v_lshl_add_u64 v[2:3], v[242:243], 0, s[20:21]
	s_mov_b32 m0, s49
	s_nop 0
	global_load_lds_dwordx4 v[2:3], off
	v_lshl_add_u64 v[2:3], v[244:245], 0, s[20:21]
	s_mov_b32 m0, s50
	s_nop 0
	global_load_lds_dwordx4 v[2:3], off
	s_waitcnt vmcnt(8)
	s_waitcnt lgkmcnt(0)
	s_barrier
	s_waitcnt lgkmcnt(0)
	v_mfma_f32_16x16x32_bf16 v[100:103], v[136:139], v[210:213], v[100:103]
	v_mfma_f32_16x16x32_bf16 v[96:99], v[144:147], v[210:213], v[96:99]
	v_mfma_f32_16x16x32_bf16 v[92:95], v[136:139], v[218:221], v[92:95]
	v_mfma_f32_16x16x32_bf16 v[88:91], v[144:147], v[218:221], v[88:91]
	s_setprio 1
	v_mfma_f32_16x16x32_bf16 v[80:83], v[136:139], v[226:229], v[80:83]
	v_mfma_f32_16x16x32_bf16 v[72:75], v[144:147], v[226:229], v[72:75]
	v_mfma_f32_16x16x32_bf16 v[60:63], v[136:139], v[234:237], v[60:63]
	v_mfma_f32_16x16x32_bf16 v[56:59], v[144:147], v[234:237], v[56:59]
	v_mfma_f32_16x16x32_bf16 v[100:103], v[140:143], v[214:217], v[100:103]
	v_mfma_f32_16x16x32_bf16 v[96:99], v[148:151], v[214:217], v[96:99]
	v_mfma_f32_16x16x32_bf16 v[92:95], v[140:143], v[222:225], v[92:95]
	v_mfma_f32_16x16x32_bf16 v[88:91], v[148:151], v[222:225], v[88:91]
	v_mfma_f32_16x16x32_bf16 v[80:83], v[140:143], v[230:233], v[80:83]
	v_mfma_f32_16x16x32_bf16 v[72:75], v[148:151], v[230:233], v[72:75]
	v_mfma_f32_16x16x32_bf16 v[60:63], v[140:143], v[238:241], v[60:63]
	v_mfma_f32_16x16x32_bf16 v[56:59], v[148:151], v[238:241], v[56:59]
	s_setprio 0
	s_setprio 1
	v_mfma_f32_16x16x32_bf16 v[36:39], v[152:155], v[210:213], v[36:39]
	v_mfma_f32_16x16x32_bf16 v[32:35], v[190:193], v[210:213], v[32:35]
	v_mfma_f32_16x16x32_bf16 v[28:31], v[152:155], v[218:221], v[28:31]
	v_mfma_f32_16x16x32_bf16 v[24:27], v[190:193], v[218:221], v[24:27]
	v_mfma_f32_16x16x32_bf16 v[20:23], v[152:155], v[226:229], v[20:23]
	v_mfma_f32_16x16x32_bf16 v[16:19], v[190:193], v[226:229], v[16:19]
	v_mfma_f32_16x16x32_bf16 v[12:15], v[152:155], v[234:237], v[12:15]
	v_mfma_f32_16x16x32_bf16 v[8:11], v[190:193], v[234:237], v[8:11]
	v_mfma_f32_16x16x32_bf16 v[36:39], v[186:189], v[214:217], v[36:39]
	v_mfma_f32_16x16x32_bf16 v[32:35], v[198:201], v[214:217], v[32:35]
	v_mfma_f32_16x16x32_bf16 v[28:31], v[186:189], v[222:225], v[28:31]
	v_mfma_f32_16x16x32_bf16 v[24:27], v[198:201], v[222:225], v[24:27]
	s_barrier
	v_mfma_f32_16x16x32_bf16 v[20:23], v[186:189], v[230:233], v[20:23]
	v_mfma_f32_16x16x32_bf16 v[16:19], v[198:201], v[230:233], v[16:19]
	v_mfma_f32_16x16x32_bf16 v[12:15], v[186:189], v[238:241], v[12:15]
	v_mfma_f32_16x16x32_bf16 v[8:11], v[198:201], v[238:241], v[8:11]
	s_setprio 0
	s_add_i32 s55, s55, 2
	s_add_u32 s8, s8, 0x100
	s_addc_u32 s9, s9, 0
	s_add_u32 s53, s53, 0x100
	s_addc_u32 s54, s54, 0
	s_cmp_gt_u32 s55, 13
	s_cbranch_scc0 .LBB0_165
	s_and_b64 vcc, exec, s[10:11]
	s_cbranch_vccz .LBB0_168
	s_barrier
	s_setprio 1

; #define PG8_STAGE(bufoff, gbase, voff) do { _Pragma("unroll") for (int _i = 0; _i < 2; ++_i) \
;         __builtin_amdgcn_global_load_lds((const unsigned*)((const char*)(gbase) + (voff)[_i]), (PG8_LAS unsigned*)(lds + (bufoff) + ldsw + _i * 8192), 16, 0, 0); } while (0)
; #define PG8_LDA(dst, b, h) do { _Pragma("unroll") for (int m = 0; m < 4; ++m) _Pragma("unroll") for (int k = 0; k < 2; ++k) dst[m][k] = *(const PG8_LAS bf16x8*)(lds + PG8_SA(b, h) + aoff + m * 2048 + k * 1024); } while (0)
; #define PG8_LDB(dst, b, h) do { _Pragma("unroll") for (int n = 0; n < 2; ++n) _Pragma("unroll") for (int k = 0; k < 2; ++k) dst[n][k] = *(const PG8_LAS bf16x8*)(lds + PG8_SB(b, h) + boff + n * 2048 + k * 1024); } while (0)
; #define PG8_MMA(ai, bj, At, Bt) do { __builtin_amdgcn_s_setprio(1); _Pragma("unroll") for (int m = 0; m < 4; ++m) _Pragma("unroll") for (int n = 0; n < 2; ++n) _Pragma("unroll") for (int k = 0; k < 2; ++k) \
;         acc[ai][bj][m][n] = __builtin_amdgcn_mfma_f32_16x16x32_bf16(Bt[n][k], At[m][k], acc[ai][bj][m][n], 0, 0, 0); __builtin_amdgcn_s_setprio(0); } while (0)
; #define PG8_WAIT_V(n) asm volatile("s_waitcnt vmcnt(" #n ")" ::: "memory")
; #define PG8_BAR __builtin_amdgcn_s_barrier()
; template <class Epi, class Sched, bool ALIGN_EPI = false, bool SP2 = false>
; __device__ __forceinline__ void gemm_phase(PG8_LAS unsigned char* lds, const Gemm g, const Sched& S, const Epi& E) {
;     ...
;         for (int t = 0; t < nt; t += 2) {
;             const bool last = (t == nt - 2);
;             const char* a1 = cA + (size_t)(t + 1) * kstep;
;             const char* a2 = last ? nA : cA + (size_t)(t + 2) * kstep; const char* b2 = last ? nB : cB + (size_t)(t + 2) * kstep;
;             const char* a3 = a2 + kstep; const char* b3 = b2 + kstep;
;             if (last && has_next) S.a_ready(nxt);
;             if constexpr (SP2) {
;             PG8_LDB(B0, 0, 0); PG8_LDB(B1, 0, 1); PG8_SCHED; PG8_LDA(At, 0, 0); PG8_STAGE(PG8_SA(1, 1), a1 + hstep, voffA);
;             PG8_WAIT_V(8); PG8_WAIT_L(0); PG8_BAR; PG8_MMA(0, 0, At, B0); PG8_MMA(0, 1, At, B1); PG8_BAR; PG8_SCHED;
;             PG8_LDA(At, 0, 1); PG8_STAGE(PG8_SB(0, 0), b2, voffB); PG8_STAGE(PG8_SB(0, 1), b2 + hstep, voffB); PG8_STAGE(PG8_SA(0, 0), a2, voffA);
;             PG8_WAIT_V(8); PG8_WAIT_L(0); PG8_BAR; PG8_MMA(1, 0, At, B0); PG8_MMA(1, 1, At, B1); PG8_BAR; PG8_SCHED;
.LBB0_203:
	s_add_i32 s36, s28, 2
	s_add_u32 s16, s24, 0x80
	s_addc_u32 s17, s25, 0
	s_add_i32 s18, 0, 0x10000
	s_cmp_eq_u32 s60, s28
	s_cselect_b32 s29, s3, s17
	s_cselect_b32 s28, s2, s16
	v_add_u32_e32 v137, s18, v200
	s_cselect_b32 s17, s9, s35
	s_cselect_b32 s16, s8, s23
	s_add_i32 s19, 0, 0x14000
	ds_read_b128 v[144:147], v137
	ds_read_b128 v[148:151], v137 offset:1024
	ds_read_b128 v[152:155], v137 offset:2048
	ds_read_b128 v[156:159], v137 offset:3072
	v_add_u32_e32 v137, s19, v200
	ds_read_b128 v[160:163], v137
	ds_read_b128 v[178:181], v137 offset:1024
	ds_read_b128 v[182:185], v137 offset:2048
	ds_read_b128 v[186:189], v137 offset:3072
	v_lshl_add_u64 v[198:199], s[24:25], 0, v[140:141]
	s_add_i32 m0, s52, 0xc000
	ds_read_b128 v[190:193], v210
	ds_read_b128 v[194:197], v210 offset:1024
	ds_read_b128 v[212:215], v210 offset:2048
	ds_read_b128 v[216:219], v210 offset:3072
	ds_read_b128 v[220:223], v210 offset:4096
	ds_read_b128 v[224:227], v210 offset:5120
	ds_read_b128 v[228:231], v210 offset:6144
	ds_read_b128 v[232:235], v210 offset:7168
	global_load_lds_dwordx4 v[198:199], off
	v_lshl_add_u64 v[198:199], s[24:25], 0, v[142:143]
	s_add_i32 m0, s52, 0xe000
	s_nop 0
	global_load_lds_dwordx4 v[198:199], off
	s_waitcnt vmcnt(8)
	s_waitcnt lgkmcnt(0)
	s_barrier
	s_waitcnt lgkmcnt(0)
	v_mfma_f32_16x16x32_bf16 v[132:135], v[144:147], v[190:193], v[132:135]
	v_mfma_f32_16x16x32_bf16 v[128:131], v[152:155], v[190:193], v[128:131]
	v_mfma_f32_16x16x32_bf16 v[116:119], v[144:147], v[212:215], v[116:119]
	v_mfma_f32_16x16x32_bf16 v[112:115], v[152:155], v[212:215], v[112:115]
	s_setprio 1
	v_mfma_f32_16x16x32_bf16 v[100:103], v[144:147], v[220:223], v[100:103]
	v_mfma_f32_16x16x32_bf16 v[96:99], v[152:155], v[220:223], v[96:99]
	v_mfma_f32_16x16x32_bf16 v[84:87], v[144:147], v[228:231], v[84:87]
	v_mfma_f32_16x16x32_bf16 v[80:83], v[152:155], v[228:231], v[80:83]
	v_mfma_f32_16x16x32_bf16 v[132:135], v[148:151], v[194:197], v[132:135]
	v_mfma_f32_16x16x32_bf16 v[128:131], v[156:159], v[194:197], v[128:131]
	v_mfma_f32_16x16x32_bf16 v[116:119], v[148:151], v[216:219], v[116:119]
	v_mfma_f32_16x16x32_bf16 v[112:115], v[156:159], v[216:219], v[112:115]
	v_mfma_f32_16x16x32_bf16 v[100:103], v[148:151], v[224:227], v[100:103]
	v_mfma_f32_16x16x32_bf16 v[96:99], v[156:159], v[224:227], v[96:99]
	v_mfma_f32_16x16x32_bf16 v[84:87], v[148:151], v[232:235], v[84:87]
	v_mfma_f32_16x16x32_bf16 v[80:83], v[156:159], v[232:235], v[80:83]
	s_setprio 0
	s_setprio 1
	v_mfma_f32_16x16x32_bf16 v[124:127], v[160:163], v[190:193], v[124:127]
	v_mfma_f32_16x16x32_bf16 v[120:123], v[182:185], v[190:193], v[120:123]
	v_mfma_f32_16x16x32_bf16 v[108:111], v[160:163], v[212:215], v[108:111]
	v_mfma_f32_16x16x32_bf16 v[104:107], v[182:185], v[212:215], v[104:107]
	v_mfma_f32_16x16x32_bf16 v[92:95], v[160:163], v[220:223], v[92:95]
	v_mfma_f32_16x16x32_bf16 v[88:91], v[182:185], v[220:223], v[88:91]
	v_mfma_f32_16x16x32_bf16 v[76:79], v[160:163], v[228:231], v[76:79]
	v_mfma_f32_16x16x32_bf16 v[72:75], v[182:185], v[228:231], v[72:75]
	v_mfma_f32_16x16x32_bf16 v[124:127], v[178:181], v[194:197], v[124:127]
	v_mfma_f32_16x16x32_bf16 v[120:123], v[186:189], v[194:197], v[120:123]
	v_mfma_f32_16x16x32_bf16 v[108:111], v[178:181], v[216:219], v[108:111]
	v_mfma_f32_16x16x32_bf16 v[104:107], v[186:189], v[216:219], v[104:107]
	s_barrier
	v_mfma_f32_16x16x32_bf16 v[92:95], v[178:181], v[224:227], v[92:95]
	v_mfma_f32_16x16x32_bf16 v[88:91], v[186:189], v[224:227], v[88:91]
	v_mfma_f32_16x16x32_bf16 v[76:79], v[178:181], v[232:235], v[76:79]
	v_mfma_f32_16x16x32_bf16 v[72:75], v[186:189], v[232:235], v[72:75]
	s_setprio 0
	s_add_i32 s18, s18, s41
	v_lshl_add_u64 v[198:199], s[16:17], 0, v[0:1]
	s_mov_b32 m0, s18
	ds_read_b128 v[190:193], v210 offset:16384
	ds_read_b128 v[194:197], v210 offset:17408
	ds_read_b128 v[212:215], v210 offset:18432
	ds_read_b128 v[216:219], v210 offset:19456
	ds_read_b128 v[220:223], v210 offset:20480
	ds_read_b128 v[224:227], v210 offset:21504
	ds_read_b128 v[228:231], v210 offset:22528
	ds_read_b128 v[232:235], v210 offset:23552
	global_load_lds_dwordx4 v[198:199], off
	s_add_i32 m0, s18, 0x2000
	v_lshl_add_u64 v[236:237], s[16:17], 0, v[2:3]
	s_add_u32 s16, s16, s12
	s_addc_u32 s17, s17, 0
	s_add_i32 s18, s19, s41
	global_load_lds_dwordx4 v[236:237], off
	v_lshl_add_u64 v[238:239], s[16:17], 0, v[0:1]
	s_mov_b32 m0, s18
	v_lshl_add_u64 v[240:241], s[16:17], 0, v[2:3]
	global_load_lds_dwordx4 v[238:239], off
	s_add_i32 m0, s18, 0x2000
	v_lshl_add_u64 v[242:243], s[28:29], 0, v[0:1]
	global_load_lds_dwordx4 v[240:241], off
	s_mov_b32 m0, s52
	v_lshl_add_u64 v[244:245], s[28:29], 0, v[2:3]
	global_load_lds_dwordx4 v[242:243], off
	s_mov_b32 m0, s53
	s_nop 0
	global_load_lds_dwordx4 v[244:245], off
	s_waitcnt vmcnt(8)
	s_waitcnt lgkmcnt(0)
	s_barrier
; #define PG8_STAGE(bufoff, gbase, voff) do { _Pragma("unroll") for (int _i = 0; _i < 2; ++_i) \
;         __builtin_amdgcn_global_load_lds((const unsigned*)((const char*)(gbase) + (voff)[_i]), (PG8_LAS unsigned*)(lds + (bufoff) + ldsw + _i * 8192), 16, 0, 0); } while (0)
; #define PG8_LDA(dst, b, h) do { _Pragma("unroll") for (int m = 0; m < 4; ++m) _Pragma("unroll") for (int k = 0; k < 2; ++k) dst[m][k] = *(const PG8_LAS bf16x8*)(lds + PG8_SA(b, h) + aoff + m * 2048 + k * 1024); } while (0)
; #define PG8_LDB(dst, b, h) do { _Pragma("unroll") for (int n = 0; n < 2; ++n) _Pragma("unroll") for (int k = 0; k < 2; ++k) dst[n][k] = *(const PG8_LAS bf16x8*)(lds + PG8_SB(b, h) + boff + n * 2048 + k * 1024); } while (0)
; #define PG8_MMA(ai, bj, At, Bt) do { __builtin_amdgcn_s_setprio(1); _Pragma("unroll") for (int m = 0; m < 4; ++m) _Pragma("unroll") for (int n = 0; n < 2; ++n) _Pragma("unroll") for (int k = 0; k < 2; ++k) \
;         acc[ai][bj][m][n] = __builtin_amdgcn_mfma_f32_16x16x32_bf16(Bt[n][k], At[m][k], acc[ai][bj][m][n], 0, 0, 0); __builtin_amdgcn_s_setprio(0); } while (0)
; #define PG8_WAIT_V(n) asm volatile("s_waitcnt vmcnt(" #n ")" ::: "memory")
; #define PG8_WAIT_L(n) asm volatile("s_waitcnt lgkmcnt(" #n ")" ::: "memory")
; #define PG8_BAR __builtin_amdgcn_s_barrier()
; #define PG8_SCHED __builtin_amdgcn_sched_barrier(0)
; template <class Epi, class Sched, bool ALIGN_EPI = false, bool SP2 = false>
; __device__ __forceinline__ void gemm_phase(PG8_LAS unsigned char* lds, const Gemm g, const Sched& S, const Epi& E) {
;     ...
;             PG8_WAIT_V(8); PG8_WAIT_L(0); PG8_BAR; PG8_MMA(1, 0, At, B0); PG8_MMA(1, 1, At, B1); PG8_BAR; PG8_SCHED;
;             PG8_LDB(B0, 1, 0); PG8_LDB(B1, 1, 1); PG8_SCHED; PG8_LDA(At, 1, 0); PG8_STAGE(PG8_SA(0, 1), a2 + hstep, voffA);
;             PG8_WAIT_V(8); PG8_WAIT_L(0); PG8_BAR; PG8_MMA(0, 0, At, B0); PG8_MMA(0, 1, At, B1); PG8_BAR; PG8_SCHED;
	s_waitcnt lgkmcnt(0)
	v_mfma_f32_16x16x32_bf16 v[68:71], v[144:147], v[190:193], v[68:71]
	v_mfma_f32_16x16x32_bf16 v[64:67], v[152:155], v[190:193], v[64:67]
	v_mfma_f32_16x16x32_bf16 v[52:55], v[144:147], v[212:215], v[52:55]
	v_mfma_f32_16x16x32_bf16 v[48:51], v[152:155], v[212:215], v[48:51]
	s_setprio 1
	v_mfma_f32_16x16x32_bf16 v[36:39], v[144:147], v[220:223], v[36:39]
	v_mfma_f32_16x16x32_bf16 v[32:35], v[152:155], v[220:223], v[32:35]
	v_mfma_f32_16x16x32_bf16 v[20:23], v[144:147], v[228:231], v[20:23]
	v_mfma_f32_16x16x32_bf16 v[16:19], v[152:155], v[228:231], v[16:19]
	v_mfma_f32_16x16x32_bf16 v[68:71], v[148:151], v[194:197], v[68:71]
	v_mfma_f32_16x16x32_bf16 v[64:67], v[156:159], v[194:197], v[64:67]
	v_mfma_f32_16x16x32_bf16 v[52:55], v[148:151], v[216:219], v[52:55]
	v_mfma_f32_16x16x32_bf16 v[48:51], v[156:159], v[216:219], v[48:51]
	v_mfma_f32_16x16x32_bf16 v[36:39], v[148:151], v[224:227], v[36:39]
	v_mfma_f32_16x16x32_bf16 v[32:35], v[156:159], v[224:227], v[32:35]
	v_mfma_f32_16x16x32_bf16 v[20:23], v[148:151], v[232:235], v[20:23]
	v_mfma_f32_16x16x32_bf16 v[16:19], v[156:159], v[232:235], v[16:19]
	s_setprio 0
	s_setprio 1
	v_mfma_f32_16x16x32_bf16 v[60:63], v[160:163], v[190:193], v[60:63]
	v_mfma_f32_16x16x32_bf16 v[56:59], v[182:185], v[190:193], v[56:59]
	v_mfma_f32_16x16x32_bf16 v[44:47], v[160:163], v[212:215], v[44:47]
	v_mfma_f32_16x16x32_bf16 v[40:43], v[182:185], v[212:215], v[40:43]
	v_mfma_f32_16x16x32_bf16 v[28:31], v[160:163], v[220:223], v[28:31]
	v_mfma_f32_16x16x32_bf16 v[24:27], v[182:185], v[220:223], v[24:27]
	v_mfma_f32_16x16x32_bf16 v[12:15], v[160:163], v[228:231], v[12:15]
	v_mfma_f32_16x16x32_bf16 v[8:11], v[182:185], v[228:231], v[8:11]
	v_mfma_f32_16x16x32_bf16 v[60:63], v[178:181], v[194:197], v[60:63]
	v_mfma_f32_16x16x32_bf16 v[56:59], v[186:189], v[194:197], v[56:59]
	v_mfma_f32_16x16x32_bf16 v[44:47], v[178:181], v[216:219], v[44:47]
	v_mfma_f32_16x16x32_bf16 v[40:43], v[186:189], v[216:219], v[40:43]
	s_barrier
	v_mfma_f32_16x16x32_bf16 v[28:31], v[178:181], v[224:227], v[28:31]
	v_mfma_f32_16x16x32_bf16 v[24:27], v[186:189], v[224:227], v[24:27]
	v_mfma_f32_16x16x32_bf16 v[12:15], v[178:181], v[232:235], v[12:15]
	v_mfma_f32_16x16x32_bf16 v[8:11], v[186:189], v[232:235], v[8:11]
	s_setprio 0
	s_add_i32 s18, 0, 0x18000
	v_add_u32_e32 v137, s18, v200
	ds_read_b128 v[144:147], v137
	ds_read_b128 v[148:151], v137 offset:1024
	ds_read_b128 v[152:155], v137 offset:2048
	ds_read_b128 v[156:159], v137 offset:3072
	v_add_u32_e32 v137, s33, v200
	ds_read_b128 v[160:163], v137
	ds_read_b128 v[178:181], v137 offset:1024
	ds_read_b128 v[182:185], v137 offset:2048
	ds_read_b128 v[186:189], v137 offset:3072
	s_add_u32 s16, s28, s12
	s_addc_u32 s17, s29, 0
	s_mov_b32 m0, s54
	v_lshl_add_u64 v[246:247], s[16:17], 0, v[0:1]
	ds_read_b128 v[190:193], v210 offset:32768
	ds_read_b128 v[194:197], v210 offset:33792
	ds_read_b128 v[212:215], v210 offset:34816
	ds_read_b128 v[216:219], v210 offset:35840
	ds_read_b128 v[220:223], v210 offset:36864
	ds_read_b128 v[224:227], v210 offset:37888
	ds_read_b128 v[228:231], v210 offset:38912
	ds_read_b128 v[232:235], v210 offset:39936
	global_load_lds_dwordx4 v[246:247], off
	v_lshl_add_u64 v[246:247], s[16:17], 0, v[2:3]
	s_mov_b32 m0, s55
	s_nop 0
	global_load_lds_dwordx4 v[246:247], off
	s_waitcnt vmcnt(8)
	s_waitcnt lgkmcnt(0)
	s_barrier
	s_waitcnt lgkmcnt(0)
	v_mfma_f32_16x16x32_bf16 v[132:135], v[144:147], v[190:193], v[132:135]
	v_mfma_f32_16x16x32_bf16 v[128:131], v[152:155], v[190:193], v[128:131]
	v_mfma_f32_16x16x32_bf16 v[116:119], v[144:147], v[212:215], v[116:119]
	v_mfma_f32_16x16x32_bf16 v[112:115], v[152:155], v[212:215], v[112:115]
	s_setprio 1
	v_mfma_f32_16x16x32_bf16 v[100:103], v[144:147], v[220:223], v[100:103]
	v_mfma_f32_16x16x32_bf16 v[96:99], v[152:155], v[220:223], v[96:99]
	v_mfma_f32_16x16x32_bf16 v[84:87], v[144:147], v[228:231], v[84:87]
	v_mfma_f32_16x16x32_bf16 v[80:83], v[152:155], v[228:231], v[80:83]
	v_mfma_f32_16x16x32_bf16 v[132:135], v[148:151], v[194:197], v[132:135]
	v_mfma_f32_16x16x32_bf16 v[128:131], v[156:159], v[194:197], v[128:131]
	v_mfma_f32_16x16x32_bf16 v[116:119], v[148:151], v[216:219], v[116:119]
	v_mfma_f32_16x16x32_bf16 v[112:115], v[156:159], v[216:219], v[112:115]
	v_mfma_f32_16x16x32_bf16 v[100:103], v[148:151], v[224:227], v[100:103]
	v_mfma_f32_16x16x32_bf16 v[96:99], v[156:159], v[224:227], v[96:99]
	v_mfma_f32_16x16x32_bf16 v[84:87], v[148:151], v[232:235], v[84:87]
	v_mfma_f32_16x16x32_bf16 v[80:83], v[156:159], v[232:235], v[80:83]
	s_setprio 0
	s_setprio 1
	v_mfma_f32_16x16x32_bf16 v[124:127], v[160:163], v[190:193], v[124:127]
	v_mfma_f32_16x16x32_bf16 v[120:123], v[182:185], v[190:193], v[120:123]
	v_mfma_f32_16x16x32_bf16 v[108:111], v[160:163], v[212:215], v[108:111]
	v_mfma_f32_16x16x32_bf16 v[104:107], v[182:185], v[212:215], v[104:107]
	v_mfma_f32_16x16x32_bf16 v[92:95], v[160:163], v[220:223], v[92:95]
	v_mfma_f32_16x16x32_bf16 v[88:91], v[182:185], v[220:223], v[88:91]
	v_mfma_f32_16x16x32_bf16 v[76:79], v[160:163], v[228:231], v[76:79]
	v_mfma_f32_16x16x32_bf16 v[72:75], v[182:185], v[228:231], v[72:75]
	v_mfma_f32_16x16x32_bf16 v[124:127], v[178:181], v[194:197], v[124:127]
	v_mfma_f32_16x16x32_bf16 v[120:123], v[186:189], v[194:197], v[120:123]
	v_mfma_f32_16x16x32_bf16 v[108:111], v[178:181], v[216:219], v[108:111]
	v_mfma_f32_16x16x32_bf16 v[104:107], v[186:189], v[216:219], v[104:107]
	s_barrier
; #define PG8_STAGE(bufoff, gbase, voff) do { _Pragma("unroll") for (int _i = 0; _i < 2; ++_i) \
;         __builtin_amdgcn_global_load_lds((const unsigned*)((const char*)(gbase) + (voff)[_i]), (PG8_LAS unsigned*)(lds + (bufoff) + ldsw + _i * 8192), 16, 0, 0); } while (0)
; #define PG8_LDA(dst, b, h) do { _Pragma("unroll") for (int m = 0; m < 4; ++m) _Pragma("unroll") for (int k = 0; k < 2; ++k) dst[m][k] = *(const PG8_LAS bf16x8*)(lds + PG8_SA(b, h) + aoff + m * 2048 + k * 1024); } while (0)
; #define PG8_MMA(ai, bj, At, Bt) do { __builtin_amdgcn_s_setprio(1); _Pragma("unroll") for (int m = 0; m < 4; ++m) _Pragma("unroll") for (int n = 0; n < 2; ++n) _Pragma("unroll") for (int k = 0; k < 2; ++k) \
;         acc[ai][bj][m][n] = __builtin_amdgcn_mfma_f32_16x16x32_bf16(Bt[n][k], At[m][k], acc[ai][bj][m][n], 0, 0, 0); __builtin_amdgcn_s_setprio(0); } while (0)
; #define PG8_WAIT_V(n) asm volatile("s_waitcnt vmcnt(" #n ")" ::: "memory")
; #define PG8_WAIT_L(n) asm volatile("s_waitcnt lgkmcnt(" #n ")" ::: "memory")
; #define PG8_BAR __builtin_amdgcn_s_barrier()
; #define PG8_SCHED __builtin_amdgcn_sched_barrier(0)
; template <class Epi, class Sched, bool ALIGN_EPI = false, bool SP2 = false>
; __device__ __forceinline__ void gemm_phase(PG8_LAS unsigned char* lds, const Gemm g, const Sched& S, const Epi& E) {
;     ...
;             PG8_WAIT_V(8); PG8_WAIT_L(0); PG8_BAR; PG8_MMA(0, 0, At, B0); PG8_MMA(0, 1, At, B1); PG8_BAR; PG8_SCHED;
;             PG8_LDA(At, 1, 1); PG8_STAGE(PG8_SB(1, 0), b3, voffB); PG8_STAGE(PG8_SB(1, 1), b3 + hstep, voffB); PG8_STAGE(PG8_SA(1, 0), a3, voffA);
;             PG8_WAIT_V(8); PG8_WAIT_L(0); PG8_BAR; PG8_MMA(1, 0, At, B0); PG8_MMA(1, 1, At, B1); PG8_BAR; PG8_SCHED;
	v_mfma_f32_16x16x32_bf16 v[92:95], v[178:181], v[224:227], v[92:95]
	v_mfma_f32_16x16x32_bf16 v[88:91], v[186:189], v[224:227], v[88:91]
	v_mfma_f32_16x16x32_bf16 v[76:79], v[178:181], v[232:235], v[76:79]
	v_mfma_f32_16x16x32_bf16 v[72:75], v[186:189], v[232:235], v[72:75]
	s_setprio 0
	s_add_i32 s16, s18, s41
	v_lshl_add_u64 v[198:199], v[198:199], 0, s[20:21]
	s_mov_b32 m0, s16
	ds_read_b128 v[190:193], v210 offset:49152
	ds_read_b128 v[194:197], v210 offset:50176
	ds_read_b128 v[212:215], v210 offset:51200
	ds_read_b128 v[216:219], v210 offset:52224
	ds_read_b128 v[220:223], v210 offset:53248
	ds_read_b128 v[224:227], v210 offset:54272
	ds_read_b128 v[228:231], v210 offset:55296
	ds_read_b128 v[232:235], v210 offset:56320
	global_load_lds_dwordx4 v[198:199], off
	v_lshl_add_u64 v[198:199], v[236:237], 0, s[20:21]
	s_add_i32 m0, s16, 0x2000
	s_add_i32 s16, s33, s41
	global_load_lds_dwordx4 v[198:199], off
	v_lshl_add_u64 v[198:199], v[238:239], 0, s[20:21]
	s_mov_b32 m0, s16
	s_nop 0
	global_load_lds_dwordx4 v[198:199], off
	v_lshl_add_u64 v[198:199], v[240:241], 0, s[20:21]
	s_add_i32 m0, s16, 0x2000
	s_nop 0
	global_load_lds_dwordx4 v[198:199], off
	v_lshl_add_u64 v[198:199], v[242:243], 0, s[20:21]
	s_mov_b32 m0, s56
	s_nop 0
	global_load_lds_dwordx4 v[198:199], off
	v_lshl_add_u64 v[198:199], v[244:245], 0, s[20:21]
	s_mov_b32 m0, s57
	s_nop 0
	global_load_lds_dwordx4 v[198:199], off
	s_waitcnt vmcnt(8)
	s_waitcnt lgkmcnt(0)
	s_barrier
	s_waitcnt lgkmcnt(0)
	v_mfma_f32_16x16x32_bf16 v[68:71], v[144:147], v[190:193], v[68:71]
	v_mfma_f32_16x16x32_bf16 v[64:67], v[152:155], v[190:193], v[64:67]
	v_mfma_f32_16x16x32_bf16 v[52:55], v[144:147], v[212:215], v[52:55]
	v_mfma_f32_16x16x32_bf16 v[48:51], v[152:155], v[212:215], v[48:51]
	s_setprio 1
	v_mfma_f32_16x16x32_bf16 v[36:39], v[144:147], v[220:223], v[36:39]
	v_mfma_f32_16x16x32_bf16 v[32:35], v[152:155], v[220:223], v[32:35]
	v_mfma_f32_16x16x32_bf16 v[20:23], v[144:147], v[228:231], v[20:23]
	v_mfma_f32_16x16x32_bf16 v[16:19], v[152:155], v[228:231], v[16:19]
	v_mfma_f32_16x16x32_bf16 v[68:71], v[148:151], v[194:197], v[68:71]
	v_mfma_f32_16x16x32_bf16 v[64:67], v[156:159], v[194:197], v[64:67]
	v_mfma_f32_16x16x32_bf16 v[52:55], v[148:151], v[216:219], v[52:55]
	v_mfma_f32_16x16x32_bf16 v[48:51], v[156:159], v[216:219], v[48:51]
	v_mfma_f32_16x16x32_bf16 v[36:39], v[148:151], v[224:227], v[36:39]
	v_mfma_f32_16x16x32_bf16 v[32:35], v[156:159], v[224:227], v[32:35]
	v_mfma_f32_16x16x32_bf16 v[20:23], v[148:151], v[232:235], v[20:23]
	v_mfma_f32_16x16x32_bf16 v[16:19], v[156:159], v[232:235], v[16:19]
	s_setprio 0
	s_setprio 1
	v_mfma_f32_16x16x32_bf16 v[60:63], v[160:163], v[190:193], v[60:63]
	v_mfma_f32_16x16x32_bf16 v[56:59], v[182:185], v[190:193], v[56:59]
	v_mfma_f32_16x16x32_bf16 v[44:47], v[160:163], v[212:215], v[44:47]
	v_mfma_f32_16x16x32_bf16 v[40:43], v[182:185], v[212:215], v[40:43]
	v_mfma_f32_16x16x32_bf16 v[28:31], v[160:163], v[220:223], v[28:31]
	v_mfma_f32_16x16x32_bf16 v[24:27], v[182:185], v[220:223], v[24:27]
	v_mfma_f32_16x16x32_bf16 v[12:15], v[160:163], v[228:231], v[12:15]
	v_mfma_f32_16x16x32_bf16 v[8:11], v[182:185], v[228:231], v[8:11]
	v_mfma_f32_16x16x32_bf16 v[60:63], v[178:181], v[194:197], v[60:63]
	v_mfma_f32_16x16x32_bf16 v[56:59], v[186:189], v[194:197], v[56:59]
	v_mfma_f32_16x16x32_bf16 v[44:47], v[178:181], v[216:219], v[44:47]
	v_mfma_f32_16x16x32_bf16 v[40:43], v[186:189], v[216:219], v[40:43]
	s_barrier
	v_mfma_f32_16x16x32_bf16 v[28:31], v[178:181], v[224:227], v[28:31]
	v_mfma_f32_16x16x32_bf16 v[24:27], v[186:189], v[224:227], v[24:27]
	v_mfma_f32_16x16x32_bf16 v[12:15], v[178:181], v[232:235], v[12:15]
	v_mfma_f32_16x16x32_bf16 v[8:11], v[186:189], v[232:235], v[8:11]
	s_setprio 0
	s_add_u32 s24, s24, 0x100
	s_addc_u32 s25, s25, 0
	s_add_u32 s23, s23, 0x100
	s_addc_u32 s35, s35, 0
	s_cmp_ge_u32 s36, s59
	s_mov_b32 s28, s36
	s_cbranch_scc0 .LBB0_203
	s_and_b64 vcc, exec, s[46:47]
	s_cbranch_vccz .LBB0_206
	s_barrier
	s_setprio 1

; #define PG8_STAGE(bufoff, gbase, voff) do { _Pragma("unroll") for (int _i = 0; _i < 2; ++_i) \
;         __builtin_amdgcn_global_load_lds((const unsigned*)((const char*)(gbase) + (voff)[_i]), (PG8_LAS unsigned*)(lds + (bufoff) + ldsw + _i * 8192), 16, 0, 0); } while (0)
; #define PG8_LDA(dst, b, h) do { _Pragma("unroll") for (int m = 0; m < 4; ++m) _Pragma("unroll") for (int k = 0; k < 2; ++k) dst[m][k] = *(const PG8_LAS bf16x8*)(lds + PG8_SA(b, h) + aoff + m * 2048 + k * 1024); } while (0)
; #define PG8_LDB(dst, b, h) do { _Pragma("unroll") for (int n = 0; n < 2; ++n) _Pragma("unroll") for (int k = 0; k < 2; ++k) dst[n][k] = *(const PG8_LAS bf16x8*)(lds + PG8_SB(b, h) + boff + n * 2048 + k * 1024); } while (0)
; #define PG8_MMA(ai, bj, At, Bt) do { __builtin_amdgcn_s_setprio(1); _Pragma("unroll") for (int m = 0; m < 4; ++m) _Pragma("unroll") for (int n = 0; n < 2; ++n) _Pragma("unroll") for (int k = 0; k < 2; ++k) \
;         acc[ai][bj][m][n] = __builtin_amdgcn_mfma_f32_16x16x32_bf16(Bt[n][k], At[m][k], acc[ai][bj][m][n], 0, 0, 0); __builtin_amdgcn_s_setprio(0); } while (0)
; #define PG8_WAIT_V(n) asm volatile("s_waitcnt vmcnt(" #n ")" ::: "memory")
; #define PG8_BAR __builtin_amdgcn_s_barrier()
; template <class Epi, class Sched, bool ALIGN_EPI = false, bool SP2 = false>
; __device__ __forceinline__ void gemm_phase(PG8_LAS unsigned char* lds, const Gemm g, const Sched& S, const Epi& E) {
;     ...
;         for (int t = 0; t < nt; t += 2) {
;             const bool last = (t == nt - 2);
;             const char* a1 = cA + (size_t)(t + 1) * kstep;
;             const char* a2 = last ? nA : cA + (size_t)(t + 2) * kstep; const char* b2 = last ? nB : cB + (size_t)(t + 2) * kstep;
;             const char* a3 = a2 + kstep; const char* b3 = b2 + kstep;
;             if (last && has_next) S.a_ready(nxt);
;             if constexpr (SP2) {
;             PG8_LDB(B0, 0, 0); PG8_LDB(B1, 0, 1); PG8_SCHED; PG8_LDA(At, 0, 0); PG8_STAGE(PG8_SA(1, 1), a1 + hstep, voffA);
;             PG8_WAIT_V(8); PG8_WAIT_L(0); PG8_BAR; PG8_MMA(0, 0, At, B0); PG8_MMA(0, 1, At, B1); PG8_BAR; PG8_SCHED;
;             PG8_LDA(At, 0, 1); PG8_STAGE(PG8_SB(0, 0), b2, voffB); PG8_STAGE(PG8_SB(0, 1), b2 + hstep, voffB); PG8_STAGE(PG8_SA(0, 0), a2, voffA);
;             PG8_WAIT_V(8); PG8_WAIT_L(0); PG8_BAR; PG8_MMA(1, 0, At, B0); PG8_MMA(1, 1, At, B1); PG8_BAR; PG8_SCHED;
.LBB0_257:
	s_add_u32 s16, s8, 0xfffc0080
	s_addc_u32 s17, s9, -1
	s_add_i32 s18, 0, 0x10000
	s_cmp_eq_u32 s55, 12
	s_cselect_b32 s43, s14, s17
	s_cselect_b32 s42, s15, s16
	v_add_u32_e32 v0, s18, v210
	s_cselect_b32 s41, s13, s54
	s_cselect_b32 s40, s25, s53
	s_add_i32 s19, 0, 0x14000
	ds_read_b128 v[104:107], v0
	ds_read_b128 v[140:143], v0 offset:1024
	ds_read_b128 v[144:147], v0 offset:2048
	ds_read_b128 v[148:151], v0 offset:3072
	v_add_u32_e32 v0, s19, v210
	ds_read_b128 v[152:155], v0
	ds_read_b128 v[156:159], v0 offset:1024
	ds_read_b128 v[160:163], v0 offset:2048
	ds_read_b128 v[192:195], v0 offset:3072
	v_lshl_add_u64 v[2:3], s[8:9], 0, v[188:189]
	s_add_i32 m0, s44, 0xc000
	ds_read_b128 v[196:199], v212
	ds_read_b128 v[214:217], v212 offset:1024
	ds_read_b128 v[218:221], v212 offset:2048
	ds_read_b128 v[222:225], v212 offset:3072
	ds_read_b128 v[226:229], v212 offset:4096
	ds_read_b128 v[230:233], v212 offset:5120
	ds_read_b128 v[234:237], v212 offset:6144
	ds_read_b128 v[238:241], v212 offset:7168
	global_load_lds_dwordx4 v[2:3], off
	v_lshl_add_u64 v[2:3], s[8:9], 0, v[190:191]
	s_add_i32 m0, s44, 0xe000
	s_nop 0
	global_load_lds_dwordx4 v[2:3], off
	s_waitcnt vmcnt(8)
	s_waitcnt lgkmcnt(0)
	s_barrier
	s_waitcnt lgkmcnt(0)
	v_mfma_f32_16x16x32_bf16 v[136:139], v[104:107], v[196:199], v[136:139]
	v_mfma_f32_16x16x32_bf16 v[128:131], v[144:147], v[196:199], v[128:131]
	v_mfma_f32_16x16x32_bf16 v[120:123], v[104:107], v[218:221], v[120:123]
	v_mfma_f32_16x16x32_bf16 v[112:115], v[144:147], v[218:221], v[112:115]
	s_setprio 1
	v_mfma_f32_16x16x32_bf16 v[100:103], v[104:107], v[226:229], v[100:103]
	v_mfma_f32_16x16x32_bf16 v[92:95], v[144:147], v[226:229], v[92:95]
	v_mfma_f32_16x16x32_bf16 v[84:87], v[104:107], v[234:237], v[84:87]
	v_mfma_f32_16x16x32_bf16 v[76:79], v[144:147], v[234:237], v[76:79]
	v_mfma_f32_16x16x32_bf16 v[136:139], v[140:143], v[214:217], v[136:139]
	v_mfma_f32_16x16x32_bf16 v[128:131], v[148:151], v[214:217], v[128:131]
	v_mfma_f32_16x16x32_bf16 v[120:123], v[140:143], v[222:225], v[120:123]
	v_mfma_f32_16x16x32_bf16 v[112:115], v[148:151], v[222:225], v[112:115]
	v_mfma_f32_16x16x32_bf16 v[100:103], v[140:143], v[230:233], v[100:103]
	v_mfma_f32_16x16x32_bf16 v[92:95], v[148:151], v[230:233], v[92:95]
	v_mfma_f32_16x16x32_bf16 v[84:87], v[140:143], v[238:241], v[84:87]
	v_mfma_f32_16x16x32_bf16 v[76:79], v[148:151], v[238:241], v[76:79]
	s_setprio 0
	s_setprio 1
	v_mfma_f32_16x16x32_bf16 v[132:135], v[152:155], v[196:199], v[132:135]
	v_mfma_f32_16x16x32_bf16 v[124:127], v[160:163], v[196:199], v[124:127]
	v_mfma_f32_16x16x32_bf16 v[116:119], v[152:155], v[218:221], v[116:119]
	v_mfma_f32_16x16x32_bf16 v[108:111], v[160:163], v[218:221], v[108:111]
	v_mfma_f32_16x16x32_bf16 v[96:99], v[152:155], v[226:229], v[96:99]
	v_mfma_f32_16x16x32_bf16 v[88:91], v[160:163], v[226:229], v[88:91]
	v_mfma_f32_16x16x32_bf16 v[80:83], v[152:155], v[234:237], v[80:83]
	v_mfma_f32_16x16x32_bf16 v[72:75], v[160:163], v[234:237], v[72:75]
	v_mfma_f32_16x16x32_bf16 v[132:135], v[156:159], v[214:217], v[132:135]
	v_mfma_f32_16x16x32_bf16 v[124:127], v[192:195], v[214:217], v[124:127]
	v_mfma_f32_16x16x32_bf16 v[116:119], v[156:159], v[222:225], v[116:119]
	v_mfma_f32_16x16x32_bf16 v[108:111], v[192:195], v[222:225], v[108:111]
	s_barrier
	v_mfma_f32_16x16x32_bf16 v[96:99], v[156:159], v[230:233], v[96:99]
	v_mfma_f32_16x16x32_bf16 v[88:91], v[192:195], v[230:233], v[88:91]
	v_mfma_f32_16x16x32_bf16 v[80:83], v[156:159], v[238:241], v[80:83]
	v_mfma_f32_16x16x32_bf16 v[72:75], v[192:195], v[238:241], v[72:75]
	s_setprio 0
	s_add_i32 s16, s18, s36
	v_lshl_add_u64 v[2:3], s[40:41], 0, v[182:183]
	s_mov_b32 m0, s16
	ds_read_b128 v[196:199], v212 offset:16384
	ds_read_b128 v[214:217], v212 offset:17408
	ds_read_b128 v[218:221], v212 offset:18432
	ds_read_b128 v[222:225], v212 offset:19456
	ds_read_b128 v[226:229], v212 offset:20480
	ds_read_b128 v[230:233], v212 offset:21504
	ds_read_b128 v[234:237], v212 offset:22528
	ds_read_b128 v[238:241], v212 offset:23552
	global_load_lds_dwordx4 v[2:3], off
	s_add_i32 m0, s16, 0x2000
	s_add_u32 s16, s40, 0x40000
	v_lshl_add_u64 v[200:201], s[40:41], 0, v[178:179]
	s_addc_u32 s17, s41, 0
	s_add_i32 s18, s19, s36
	global_load_lds_dwordx4 v[200:201], off
	v_lshl_add_u64 v[242:243], s[16:17], 0, v[182:183]
	s_mov_b32 m0, s18
	v_lshl_add_u64 v[244:245], s[42:43], 0, v[180:181]
	global_load_lds_dwordx4 v[242:243], off
	v_lshl_add_u64 v[242:243], s[16:17], 0, v[178:179]
	s_add_i32 m0, s18, 0x2000
	s_nop 0
	global_load_lds_dwordx4 v[242:243], off
	v_lshl_add_u64 v[242:243], s[42:43], 0, v[184:185]
	s_mov_b32 m0, s44
	s_nop 0
	global_load_lds_dwordx4 v[242:243], off
	s_mov_b32 m0, s45
	s_nop 0
	global_load_lds_dwordx4 v[244:245], off
	s_waitcnt vmcnt(8)
	s_waitcnt lgkmcnt(0)
	s_barrier
; #define PG8_STAGE(bufoff, gbase, voff) do { _Pragma("unroll") for (int _i = 0; _i < 2; ++_i) \
;         __builtin_amdgcn_global_load_lds((const unsigned*)((const char*)(gbase) + (voff)[_i]), (PG8_LAS unsigned*)(lds + (bufoff) + ldsw + _i * 8192), 16, 0, 0); } while (0)
; #define PG8_LDA(dst, b, h) do { _Pragma("unroll") for (int m = 0; m < 4; ++m) _Pragma("unroll") for (int k = 0; k < 2; ++k) dst[m][k] = *(const PG8_LAS bf16x8*)(lds + PG8_SA(b, h) + aoff + m * 2048 + k * 1024); } while (0)
; #define PG8_LDB(dst, b, h) do { _Pragma("unroll") for (int n = 0; n < 2; ++n) _Pragma("unroll") for (int k = 0; k < 2; ++k) dst[n][k] = *(const PG8_LAS bf16x8*)(lds + PG8_SB(b, h) + boff + n * 2048 + k * 1024); } while (0)
; #define PG8_MMA(ai, bj, At, Bt) do { __builtin_amdgcn_s_setprio(1); _Pragma("unroll") for (int m = 0; m < 4; ++m) _Pragma("unroll") for (int n = 0; n < 2; ++n) _Pragma("unroll") for (int k = 0; k < 2; ++k) \
;         acc[ai][bj][m][n] = __builtin_amdgcn_mfma_f32_16x16x32_bf16(Bt[n][k], At[m][k], acc[ai][bj][m][n], 0, 0, 0); __builtin_amdgcn_s_setprio(0); } while (0)
; #define PG8_WAIT_V(n) asm volatile("s_waitcnt vmcnt(" #n ")" ::: "memory")
; #define PG8_WAIT_L(n) asm volatile("s_waitcnt lgkmcnt(" #n ")" ::: "memory")
; #define PG8_BAR __builtin_amdgcn_s_barrier()
; #define PG8_SCHED __builtin_amdgcn_sched_barrier(0)
; template <class Epi, class Sched, bool ALIGN_EPI = false, bool SP2 = false>
; __device__ __forceinline__ void gemm_phase(PG8_LAS unsigned char* lds, const Gemm g, const Sched& S, const Epi& E) {
;     ...
;             PG8_WAIT_V(8); PG8_WAIT_L(0); PG8_BAR; PG8_MMA(1, 0, At, B0); PG8_MMA(1, 1, At, B1); PG8_BAR; PG8_SCHED;
;             PG8_LDB(B0, 1, 0); PG8_LDB(B1, 1, 1); PG8_SCHED; PG8_LDA(At, 1, 0); PG8_STAGE(PG8_SA(0, 1), a2 + hstep, voffA);
;             PG8_WAIT_V(8); PG8_WAIT_L(0); PG8_BAR; PG8_MMA(0, 0, At, B0); PG8_MMA(0, 1, At, B1); PG8_BAR; PG8_SCHED;
	s_waitcnt lgkmcnt(0)
	v_mfma_f32_16x16x32_bf16 v[68:71], v[104:107], v[196:199], v[68:71]
	v_mfma_f32_16x16x32_bf16 v[60:63], v[144:147], v[196:199], v[60:63]
	v_mfma_f32_16x16x32_bf16 v[52:55], v[104:107], v[218:221], v[52:55]
	v_mfma_f32_16x16x32_bf16 v[44:47], v[144:147], v[218:221], v[44:47]
	s_setprio 1
	v_mfma_f32_16x16x32_bf16 v[36:39], v[104:107], v[226:229], v[36:39]
	v_mfma_f32_16x16x32_bf16 v[28:31], v[144:147], v[226:229], v[28:31]
	v_mfma_f32_16x16x32_bf16 v[20:23], v[104:107], v[234:237], v[20:23]
	v_mfma_f32_16x16x32_bf16 v[12:15], v[144:147], v[234:237], v[12:15]
	v_mfma_f32_16x16x32_bf16 v[68:71], v[140:143], v[214:217], v[68:71]
	v_mfma_f32_16x16x32_bf16 v[60:63], v[148:151], v[214:217], v[60:63]
	v_mfma_f32_16x16x32_bf16 v[52:55], v[140:143], v[222:225], v[52:55]
	v_mfma_f32_16x16x32_bf16 v[44:47], v[148:151], v[222:225], v[44:47]
	v_mfma_f32_16x16x32_bf16 v[36:39], v[140:143], v[230:233], v[36:39]
	v_mfma_f32_16x16x32_bf16 v[28:31], v[148:151], v[230:233], v[28:31]
	v_mfma_f32_16x16x32_bf16 v[20:23], v[140:143], v[238:241], v[20:23]
	v_mfma_f32_16x16x32_bf16 v[12:15], v[148:151], v[238:241], v[12:15]
	s_setprio 0
	s_setprio 1
	v_mfma_f32_16x16x32_bf16 v[64:67], v[152:155], v[196:199], v[64:67]
	v_mfma_f32_16x16x32_bf16 v[56:59], v[160:163], v[196:199], v[56:59]
	v_mfma_f32_16x16x32_bf16 v[48:51], v[152:155], v[218:221], v[48:51]
	v_mfma_f32_16x16x32_bf16 v[40:43], v[160:163], v[218:221], v[40:43]
	v_mfma_f32_16x16x32_bf16 v[32:35], v[152:155], v[226:229], v[32:35]
	v_mfma_f32_16x16x32_bf16 v[24:27], v[160:163], v[226:229], v[24:27]
	v_mfma_f32_16x16x32_bf16 v[16:19], v[152:155], v[234:237], v[16:19]
	v_mfma_f32_16x16x32_bf16 v[8:11], v[160:163], v[234:237], v[8:11]
	v_mfma_f32_16x16x32_bf16 v[64:67], v[156:159], v[214:217], v[64:67]
	v_mfma_f32_16x16x32_bf16 v[56:59], v[192:195], v[214:217], v[56:59]
	v_mfma_f32_16x16x32_bf16 v[48:51], v[156:159], v[222:225], v[48:51]
	v_mfma_f32_16x16x32_bf16 v[40:43], v[192:195], v[222:225], v[40:43]
	s_barrier
	v_mfma_f32_16x16x32_bf16 v[32:35], v[156:159], v[230:233], v[32:35]
	v_mfma_f32_16x16x32_bf16 v[24:27], v[192:195], v[230:233], v[24:27]
	v_mfma_f32_16x16x32_bf16 v[16:19], v[156:159], v[238:241], v[16:19]
	v_mfma_f32_16x16x32_bf16 v[8:11], v[192:195], v[238:241], v[8:11]
	s_setprio 0
	s_add_i32 s18, 0, 0x18000
	v_add_u32_e32 v0, s18, v210
	ds_read_b128 v[104:107], v0
	ds_read_b128 v[140:143], v0 offset:1024
	ds_read_b128 v[144:147], v0 offset:2048
	ds_read_b128 v[148:151], v0 offset:3072
	v_add_u32_e32 v0, s33, v210
	ds_read_b128 v[152:155], v0
	ds_read_b128 v[156:159], v0 offset:1024
	ds_read_b128 v[160:163], v0 offset:2048
	ds_read_b128 v[192:195], v0 offset:3072
	s_add_u32 s16, s42, 0x40000
	s_addc_u32 s17, s43, 0
	s_mov_b32 m0, s46
	v_lshl_add_u64 v[246:247], s[16:17], 0, v[184:185]
	ds_read_b128 v[196:199], v212 offset:32768
	ds_read_b128 v[214:217], v212 offset:33792
	ds_read_b128 v[218:221], v212 offset:34816
	ds_read_b128 v[222:225], v212 offset:35840
	ds_read_b128 v[226:229], v212 offset:36864
	ds_read_b128 v[230:233], v212 offset:37888
	ds_read_b128 v[234:237], v212 offset:38912
	ds_read_b128 v[238:241], v212 offset:39936
	global_load_lds_dwordx4 v[246:247], off
	v_lshl_add_u64 v[246:247], s[16:17], 0, v[180:181]
	s_mov_b32 m0, s47
	s_nop 0
	global_load_lds_dwordx4 v[246:247], off
	s_waitcnt vmcnt(8)
	s_waitcnt lgkmcnt(0)
	s_barrier
	s_waitcnt lgkmcnt(0)
	v_mfma_f32_16x16x32_bf16 v[136:139], v[104:107], v[196:199], v[136:139]
	v_mfma_f32_16x16x32_bf16 v[128:131], v[144:147], v[196:199], v[128:131]
	v_mfma_f32_16x16x32_bf16 v[120:123], v[104:107], v[218:221], v[120:123]
	v_mfma_f32_16x16x32_bf16 v[112:115], v[144:147], v[218:221], v[112:115]
	s_setprio 1
	v_mfma_f32_16x16x32_bf16 v[100:103], v[104:107], v[226:229], v[100:103]
	v_mfma_f32_16x16x32_bf16 v[92:95], v[144:147], v[226:229], v[92:95]
	v_mfma_f32_16x16x32_bf16 v[84:87], v[104:107], v[234:237], v[84:87]
	v_mfma_f32_16x16x32_bf16 v[76:79], v[144:147], v[234:237], v[76:79]
	v_mfma_f32_16x16x32_bf16 v[136:139], v[140:143], v[214:217], v[136:139]
	v_mfma_f32_16x16x32_bf16 v[128:131], v[148:151], v[214:217], v[128:131]
	v_mfma_f32_16x16x32_bf16 v[120:123], v[140:143], v[222:225], v[120:123]
	v_mfma_f32_16x16x32_bf16 v[112:115], v[148:151], v[222:225], v[112:115]
	v_mfma_f32_16x16x32_bf16 v[100:103], v[140:143], v[230:233], v[100:103]
	v_mfma_f32_16x16x32_bf16 v[92:95], v[148:151], v[230:233], v[92:95]
	v_mfma_f32_16x16x32_bf16 v[84:87], v[140:143], v[238:241], v[84:87]
	v_mfma_f32_16x16x32_bf16 v[76:79], v[148:151], v[238:241], v[76:79]
	s_setprio 0
	s_setprio 1
	v_mfma_f32_16x16x32_bf16 v[132:135], v[152:155], v[196:199], v[132:135]
	v_mfma_f32_16x16x32_bf16 v[124:127], v[160:163], v[196:199], v[124:127]
	v_mfma_f32_16x16x32_bf16 v[116:119], v[152:155], v[218:221], v[116:119]
	v_mfma_f32_16x16x32_bf16 v[108:111], v[160:163], v[218:221], v[108:111]
	v_mfma_f32_16x16x32_bf16 v[96:99], v[152:155], v[226:229], v[96:99]
	v_mfma_f32_16x16x32_bf16 v[88:91], v[160:163], v[226:229], v[88:91]
	v_mfma_f32_16x16x32_bf16 v[80:83], v[152:155], v[234:237], v[80:83]
	v_mfma_f32_16x16x32_bf16 v[72:75], v[160:163], v[234:237], v[72:75]
	v_mfma_f32_16x16x32_bf16 v[132:135], v[156:159], v[214:217], v[132:135]
	v_mfma_f32_16x16x32_bf16 v[124:127], v[192:195], v[214:217], v[124:127]
	v_mfma_f32_16x16x32_bf16 v[116:119], v[156:159], v[222:225], v[116:119]
	v_mfma_f32_16x16x32_bf16 v[108:111], v[192:195], v[222:225], v[108:111]
	s_barrier
; #define PG8_STAGE(bufoff, gbase, voff) do { _Pragma("unroll") for (int _i = 0; _i < 2; ++_i) \
;         __builtin_amdgcn_global_load_lds((const unsigned*)((const char*)(gbase) + (voff)[_i]), (PG8_LAS unsigned*)(lds + (bufoff) + ldsw + _i * 8192), 16, 0, 0); } while (0)
; #define PG8_LDA(dst, b, h) do { _Pragma("unroll") for (int m = 0; m < 4; ++m) _Pragma("unroll") for (int k = 0; k < 2; ++k) dst[m][k] = *(const PG8_LAS bf16x8*)(lds + PG8_SA(b, h) + aoff + m * 2048 + k * 1024); } while (0)
; #define PG8_MMA(ai, bj, At, Bt) do { __builtin_amdgcn_s_setprio(1); _Pragma("unroll") for (int m = 0; m < 4; ++m) _Pragma("unroll") for (int n = 0; n < 2; ++n) _Pragma("unroll") for (int k = 0; k < 2; ++k) \
;         acc[ai][bj][m][n] = __builtin_amdgcn_mfma_f32_16x16x32_bf16(Bt[n][k], At[m][k], acc[ai][bj][m][n], 0, 0, 0); __builtin_amdgcn_s_setprio(0); } while (0)
; #define PG8_WAIT_V(n) asm volatile("s_waitcnt vmcnt(" #n ")" ::: "memory")
; #define PG8_WAIT_L(n) asm volatile("s_waitcnt lgkmcnt(" #n ")" ::: "memory")
; #define PG8_BAR __builtin_amdgcn_s_barrier()
; #define PG8_SCHED __builtin_amdgcn_sched_barrier(0)
; template <class Epi, class Sched, bool ALIGN_EPI = false, bool SP2 = false>
; __device__ __forceinline__ void gemm_phase(PG8_LAS unsigned char* lds, const Gemm g, const Sched& S, const Epi& E) {
;     ...
;             PG8_WAIT_V(8); PG8_WAIT_L(0); PG8_BAR; PG8_MMA(0, 0, At, B0); PG8_MMA(0, 1, At, B1); PG8_BAR; PG8_SCHED;
;             PG8_LDA(At, 1, 1); PG8_STAGE(PG8_SB(1, 0), b3, voffB); PG8_STAGE(PG8_SB(1, 1), b3 + hstep, voffB); PG8_STAGE(PG8_SA(1, 0), a3, voffA);
;             PG8_WAIT_V(8); PG8_WAIT_L(0); PG8_BAR; PG8_MMA(1, 0, At, B0); PG8_MMA(1, 1, At, B1); PG8_BAR; PG8_SCHED;
	v_mfma_f32_16x16x32_bf16 v[96:99], v[156:159], v[230:233], v[96:99]
	v_mfma_f32_16x16x32_bf16 v[88:91], v[192:195], v[230:233], v[88:91]
	v_mfma_f32_16x16x32_bf16 v[80:83], v[156:159], v[238:241], v[80:83]
	v_mfma_f32_16x16x32_bf16 v[72:75], v[192:195], v[238:241], v[72:75]
	s_setprio 0
	s_add_i32 s16, s18, s36
	v_lshl_add_u64 v[2:3], v[2:3], 0, s[20:21]
	s_mov_b32 m0, s16
	ds_read_b128 v[196:199], v212 offset:49152
	ds_read_b128 v[214:217], v212 offset:50176
	ds_read_b128 v[218:221], v212 offset:51200
	ds_read_b128 v[222:225], v212 offset:52224
	ds_read_b128 v[226:229], v212 offset:53248
	ds_read_b128 v[230:233], v212 offset:54272
	ds_read_b128 v[234:237], v212 offset:55296
	ds_read_b128 v[238:241], v212 offset:56320
	global_load_lds_dwordx4 v[2:3], off
	s_add_i32 m0, s16, 0x2000
	s_add_u32 s16, s40, 0x40080
	v_lshl_add_u64 v[2:3], v[200:201], 0, s[20:21]
	s_addc_u32 s17, s41, 0
	s_add_i32 s18, s33, s36
	global_load_lds_dwordx4 v[2:3], off
	v_lshl_add_u64 v[2:3], s[16:17], 0, v[182:183]
	s_mov_b32 m0, s18
	s_nop 0
	global_load_lds_dwordx4 v[2:3], off
	v_lshl_add_u64 v[2:3], s[16:17], 0, v[178:179]
	s_add_i32 m0, s18, 0x2000
	s_nop 0
	global_load_lds_dwordx4 v[2:3], off
	v_lshl_add_u64 v[2:3], v[242:243], 0, s[20:21]
	s_mov_b32 m0, s48
	s_nop 0
	global_load_lds_dwordx4 v[2:3], off
	v_lshl_add_u64 v[2:3], v[244:245], 0, s[20:21]
	s_mov_b32 m0, s49
	s_nop 0
	global_load_lds_dwordx4 v[2:3], off
	s_waitcnt vmcnt(8)
	s_waitcnt lgkmcnt(0)
	s_barrier
	s_waitcnt lgkmcnt(0)
	v_mfma_f32_16x16x32_bf16 v[68:71], v[104:107], v[196:199], v[68:71]
	v_mfma_f32_16x16x32_bf16 v[60:63], v[144:147], v[196:199], v[60:63]
	v_mfma_f32_16x16x32_bf16 v[52:55], v[104:107], v[218:221], v[52:55]
	v_mfma_f32_16x16x32_bf16 v[44:47], v[144:147], v[218:221], v[44:47]
	s_setprio 1
	v_mfma_f32_16x16x32_bf16 v[36:39], v[104:107], v[226:229], v[36:39]
	v_mfma_f32_16x16x32_bf16 v[28:31], v[144:147], v[226:229], v[28:31]
	v_mfma_f32_16x16x32_bf16 v[20:23], v[104:107], v[234:237], v[20:23]
	v_mfma_f32_16x16x32_bf16 v[12:15], v[144:147], v[234:237], v[12:15]
	v_mfma_f32_16x16x32_bf16 v[68:71], v[140:143], v[214:217], v[68:71]
	v_mfma_f32_16x16x32_bf16 v[60:63], v[148:151], v[214:217], v[60:63]
	v_mfma_f32_16x16x32_bf16 v[52:55], v[140:143], v[222:225], v[52:55]
	v_mfma_f32_16x16x32_bf16 v[44:47], v[148:151], v[222:225], v[44:47]
	v_mfma_f32_16x16x32_bf16 v[36:39], v[140:143], v[230:233], v[36:39]
	v_mfma_f32_16x16x32_bf16 v[28:31], v[148:151], v[230:233], v[28:31]
	v_mfma_f32_16x16x32_bf16 v[20:23], v[140:143], v[238:241], v[20:23]
	v_mfma_f32_16x16x32_bf16 v[12:15], v[148:151], v[238:241], v[12:15]
	s_setprio 0
	s_setprio 1
	v_mfma_f32_16x16x32_bf16 v[64:67], v[152:155], v[196:199], v[64:67]
	v_mfma_f32_16x16x32_bf16 v[56:59], v[160:163], v[196:199], v[56:59]
	v_mfma_f32_16x16x32_bf16 v[48:51], v[152:155], v[218:221], v[48:51]
	v_mfma_f32_16x16x32_bf16 v[40:43], v[160:163], v[218:221], v[40:43]
	v_mfma_f32_16x16x32_bf16 v[32:35], v[152:155], v[226:229], v[32:35]
	v_mfma_f32_16x16x32_bf16 v[24:27], v[160:163], v[226:229], v[24:27]
	v_mfma_f32_16x16x32_bf16 v[16:19], v[152:155], v[234:237], v[16:19]
	v_mfma_f32_16x16x32_bf16 v[8:11], v[160:163], v[234:237], v[8:11]
	v_mfma_f32_16x16x32_bf16 v[64:67], v[156:159], v[214:217], v[64:67]
	v_mfma_f32_16x16x32_bf16 v[56:59], v[192:195], v[214:217], v[56:59]
	v_mfma_f32_16x16x32_bf16 v[48:51], v[156:159], v[222:225], v[48:51]
	v_mfma_f32_16x16x32_bf16 v[40:43], v[192:195], v[222:225], v[40:43]
	s_barrier
	v_mfma_f32_16x16x32_bf16 v[32:35], v[156:159], v[230:233], v[32:35]
	v_mfma_f32_16x16x32_bf16 v[24:27], v[192:195], v[230:233], v[24:27]
	v_mfma_f32_16x16x32_bf16 v[16:19], v[156:159], v[238:241], v[16:19]
	v_mfma_f32_16x16x32_bf16 v[8:11], v[192:195], v[238:241], v[8:11]
	s_setprio 0
	s_add_i32 s55, s55, 2
	s_add_u32 s8, s8, 0x100
	s_addc_u32 s9, s9, 0
	s_add_u32 s53, s53, 0x100
	s_addc_u32 s54, s54, 0
	s_cmp_gt_u32 s55, 13
	s_cbranch_scc0 .LBB0_257
	s_and_b64 vcc, exec, s[10:11]
	s_cbranch_vccz .LBB0_260
	s_barrier
	s_setprio 1
